# bounded next-layer weight-conversion helper calls at the end of E_GU (2 tiles) and E_IN (3 tiles) for workgroups that have fewer GEMM tiles than the phase maximum
# speedup vs baseline: 1.0166x; 1.0166x over previous
.LBB0_354:
	s_mov_b32 s99, 0x7fffffff
	s_cmp_eq_u32 s27, 5
	s_cbranch_scc0 .Lh_n5
	s_and_b32 s98, s74, 7
	s_cmp_lt_u32 s98, 4
	s_cbranch_scc0 .Lh_help5
	s_lshr_b32 s98, s74, 6
	s_cmp_lt_u32 s98, 4
	s_cbranch_scc1 .Lh_norm
.Lh_help5:
	s_mov_b32 s10, 3
	s_mov_b32 s99, 2
	s_branch .LBB0_365
.Lh_n5:
	s_cmp_eq_u32 s27, 0
	s_cbranch_scc0 .Lh_n0
	s_and_b32 s98, s74, 7
	s_cmp_lt_u32 s98, 2
	s_cbranch_scc1 .Lh_norm
	s_lshr_b32 s98, s74, 6
	s_cmp_lt_u32 s98, 4
	s_cbranch_scc1 .Lh_norm
	s_mov_b32 s10, 1
	s_mov_b32 s99, 3
	s_branch .LBB0_365
.Lh_n0:
.Lh_norm:
	s_cmp_lt_i32 s27, 4
	s_cbranch_scc1 .LBB0_357
	s_cmp_gt_i32 s27, 5
	s_cbranch_scc0 .LBB0_358
	s_cmp_eq_u32 s27, 6
	s_cselect_b64 s[0:1], -1, 0
	s_cbranch_execz .LBB0_359
	s_branch .LBB0_360

.LBB0_371:
	s_cmp_eq_u32 s99, 0
	s_cbranch_scc1 .LBB0_412
	s_add_i32 s99, s99, -1
	s_barrier
	s_and_saveexec_b64 s[34:35], s[36:37]
	s_cbranch_execz .LBB0_375
	s_mov_b64 s[66:67], exec
	v_mbcnt_lo_u32_b32 v7, s66, 0
	v_mbcnt_hi_u32_b32 v7, s67, v7
	v_cmp_eq_u32_e32 vcc, 0, v7
	s_and_saveexec_b64 s[64:65], vcc
	s_cbranch_execz .LBB0_374
	s_bcnt1_i32_b64 s66, s[66:67]
	v_mov_b32_e32 v8, s66
	global_atomic_add v8, v117, v8, s[0:1] sc0
